# v26: v25 + l0 token, qkv and mixer phases write-through with flat barriers
# baseline (speedup 1.0000x reference)
.LBB0_657:
	s_cmp_lt_i32 s59, 5
	s_barrier
	s_cbranch_scc1 .LBB0_711
	s_waitcnt vmcnt(0)
	s_barrier
	s_and_saveexec_b64 s[2:3], s[0:1]
	s_cbranch_execz .LBB0_710
	s_waitcnt vmcnt(0) lgkmcnt(0)
	v_mov_b32_e32 v241, 0
	v_lshlrev_b32_e64 v254, 8, s31
	v_mov_b32_e32 v247, 1
	v_mov_b32_e32 v246, 0x3600
	global_atomic_add v248, v246, v247, s[60:61] sc0

.LBB0_986:
	s_cmp_lt_i32 s59, 7
	s_barrier
	s_cbranch_scc1 .LBB0_1040
	s_waitcnt vmcnt(0)
	s_barrier
	s_and_saveexec_b64 s[2:3], s[0:1]
	s_cbranch_execz .LBB0_1039
	s_waitcnt vmcnt(0) lgkmcnt(0)
	v_mov_b32_e32 v241, 0
	v_lshlrev_b32_e64 v254, 8, s31
	v_mov_b32_e32 v247, 1
	v_mov_b32_e32 v246, 0x3600
	global_atomic_add v248, v246, v247, s[60:61] sc0

.LBB0_1106:
	s_cmp_lt_i32 s59, 8
	s_barrier
	s_cbranch_scc1 .LBB0_1160
	s_waitcnt vmcnt(0)
	s_barrier
	s_and_saveexec_b64 s[2:3], s[0:1]
	s_cbranch_execz .LBB0_1159
	s_waitcnt vmcnt(0) lgkmcnt(0)
	v_mov_b32_e32 v241, 0
	v_lshlrev_b32_e64 v254, 8, s31
	v_mov_b32_e32 v247, 1
	v_mov_b32_e32 v246, 0x3600
	global_atomic_add v248, v246, v247, s[60:61] sc0
